# v47 plus spatial-gating LayerNorm stage: second batch of ln_w/ln_b loads issued together with the first (one dependent round trip fewer per item)
# baseline (speedup 1.0000x reference)
; DI unsigned pk2(float lo, float hi) { f32x2 v = {lo, hi}; bf16v2 r = __builtin_convertvector(v, bf16v2); return __builtin_bit_cast(unsigned, r); }
; DI float bflo(unsigned w) { return __uint_as_float(w << 16); }
; DI float bfhi(unsigned w) { return __uint_as_float(w & 0xffff0000u); }
; DI void phase_spatial(LAS unsigned char* lds, const bf16_t* GV, bf16_t* UG, const f32x2* STATS, const float* ln_w, const float* ln_b, const float* w_s, const float* b_s, int G) {
;     ...
;             const int s = tid >> 2, cq = tid & 3; const f32x2 st = STATS[rowbase + s];
;             const bf16_t* p = GV + (rowbase + s) * D + 128 * g + 32 * cq;
; #pragma unroll
;             for (int q = 0; q < 4; ++q) { const u32x4 a = *(const u32x4*)(p + 8 * q); const unsigned aw[4] = {a.x, a.y, a.z, a.w};
;                 const f32x4 w0 = *(const f32x4*)(ln_w + 128 * g + 32 * cq + 8 * q), w1 = *(const f32x4*)(ln_w + 128 * g + 32 * cq + 8 * q + 4);
;                 const f32x4 c0 = *(const f32x4*)(ln_b + 128 * g + 32 * cq + 8 * q), c1 = *(const f32x4*)(ln_b + 128 * g + 32 * cq + 8 * q + 4);
;                 const float wv[8] = {w0.x, w0.y, w0.z, w0.w, w1.x, w1.y, w1.z, w1.w}, bv[8] = {c0.x, c0.y, c0.z, c0.w, c1.x, c1.y, c1.z, c1.w};
; #pragma unroll
;                 for (int w = 0; w < 4; ++w) { const float y0 = (bflo(aw[w]) - st.x) * st.y * wv[2 * w] + bv[2 * w], y1 = (bfhi(aw[w]) - st.x) * st.y * wv[2 * w + 1] + bv[2 * w + 1];
;                     const unsigned pk = pk2(y0, y1); const int cc = 32 * cq + 8 * q + 2 * w;
;                     VL[cc * 136 + s] = (bf16_t)(pk & 0xffffu); VL[(cc + 1) * 136 + s] = (bf16_t)(pk >> 16); } }
.LBB0_136:
	s_ashr_i32 s10, s15, 8
	s_ashr_i32 s11, s10, 31
	s_lshl_b64 s[10:11], s[10:11], 12
	s_and_b32 s12, s14, 0xf80
	s_or_b32 s10, s10, s12
	v_lshl_add_u64 v[0:1], s[10:11], 0, v[40:41]
	s_and_b32 s17, s15, 7
	v_lshl_add_u64 v[2:3], v[0:1], 3, s[96:97]
	v_lshlrev_b64 v[0:1], 11, v[0:1]
	v_lshl_add_u64 v[0:1], s[76:77], 0, v[0:1]
	s_lshl_b32 s18, s17, 8
	s_mov_b32 s19, s72
	s_barrier
	global_load_dwordx2 v[54:55], v[2:3], off
	v_lshl_add_u64 v[0:1], v[0:1], 0, s[18:19]
	v_lshl_add_u64 v[12:13], v[0:1], 0, v[48:49]
	s_lshl_b32 s18, s17, 9
	v_lshl_add_u64 v[38:39], v[42:43], 0, s[18:19]
	v_lshl_add_u64 v[36:37], v[44:45], 0, s[18:19]
	global_load_dwordx4 v[0:3], v[12:13], off offset:48
	global_load_dwordx4 v[4:7], v[12:13], off offset:32
	global_load_dwordx4 v[8:11], v[12:13], off offset:16
	s_nop 0
	global_load_dwordx4 v[12:15], v[12:13], off
	s_nop 0
	global_load_dwordx4 v[16:19], v[38:39], off offset:48
	global_load_dwordx4 v[20:23], v[38:39], off offset:32
	global_load_dwordx4 v[24:27], v[38:39], off offset:16
	global_load_dwordx4 v[28:31], v[38:39], off
	global_load_dwordx4 v[32:35], v[36:37], off offset:48
	global_load_dwordx4 v[64:67], v[36:37], off offset:32
	global_load_dwordx4 v[68:71], v[36:37], off offset:16
	global_load_dwordx4 v[72:75], v[36:37], off
	global_load_dwordx4 v[80:83], v[38:39], off offset:112
	global_load_dwordx4 v[84:87], v[38:39], off offset:96
	global_load_dwordx4 v[88:91], v[38:39], off offset:80
	global_load_dwordx4 v[92:95], v[38:39], off offset:64
	global_load_dwordx4 v[96:99], v[36:37], off offset:112
	global_load_dwordx4 v[100:103], v[36:37], off offset:96
	global_load_dwordx4 v[104:107], v[36:37], off offset:80
	global_load_dwordx4 v[108:111], v[36:37], off offset:64
	s_lshl_b32 s12, s17, 7
	s_cmp_eq_u32 s17, s16
	s_waitcnt vmcnt(16)
	v_lshlrev_b32_e32 v76, 16, v12
	v_and_b32_e32 v77, 0xffff0000, v12
	v_pk_add_f32 v[76:77], v[76:77], v[54:55] op_sel_hi:[1,0] neg_lo:[0,1] neg_hi:[0,1]
	s_nop 0
	v_pk_mul_f32 v[76:77], v[54:55], v[76:77] op_sel:[1,0]
	s_waitcnt vmcnt(8)
	v_pk_fma_f32 v[28:29], v[28:29], v[76:77], v[72:73]
	s_nop 0
	v_cvt_pk_bf16_f32 v12, v28, v29
	ds_write_b16 v58, v12
	ds_write_b16_d16_hi v58, v12 offset:272
	v_lshlrev_b32_e32 v12, 16, v13
	v_and_b32_e32 v13, 0xffff0000, v13
	v_pk_add_f32 v[12:13], v[12:13], v[54:55] op_sel_hi:[1,0] neg_lo:[0,1] neg_hi:[0,1]
	s_nop 0
	v_pk_mul_f32 v[12:13], v[54:55], v[12:13] op_sel:[1,0]
	s_nop 0
	v_pk_fma_f32 v[12:13], v[30:31], v[12:13], v[74:75]
	s_nop 0
	v_cvt_pk_bf16_f32 v12, v12, v13
	ds_write_b16 v58, v12 offset:544
	ds_write_b16_d16_hi v58, v12 offset:816
	v_lshlrev_b32_e32 v12, 16, v14
	v_and_b32_e32 v13, 0xffff0000, v14
	v_pk_add_f32 v[12:13], v[12:13], v[54:55] op_sel_hi:[1,0] neg_lo:[0,1] neg_hi:[0,1]
	s_nop 0
	v_pk_mul_f32 v[12:13], v[54:55], v[12:13] op_sel:[1,0]
	s_nop 0
	v_pk_fma_f32 v[12:13], v[24:25], v[12:13], v[68:69]
	s_nop 0
	v_cvt_pk_bf16_f32 v12, v12, v13
	ds_write_b16 v58, v12 offset:1088
	ds_write_b16_d16_hi v58, v12 offset:1360
	v_lshlrev_b32_e32 v12, 16, v15
	v_and_b32_e32 v13, 0xffff0000, v15
	v_pk_add_f32 v[12:13], v[12:13], v[54:55] op_sel_hi:[1,0] neg_lo:[0,1] neg_hi:[0,1]
	s_nop 0
	v_pk_mul_f32 v[12:13], v[54:55], v[12:13] op_sel:[1,0]
	s_nop 0
	v_pk_fma_f32 v[12:13], v[26:27], v[12:13], v[70:71]
	s_nop 0
	v_cvt_pk_bf16_f32 v12, v12, v13
	ds_write_b16 v58, v12 offset:1632
	ds_write_b16_d16_hi v58, v12 offset:1904
	v_lshlrev_b32_e32 v12, 16, v8
	v_and_b32_e32 v13, 0xffff0000, v8
	v_pk_add_f32 v[12:13], v[12:13], v[54:55] op_sel_hi:[1,0] neg_lo:[0,1] neg_hi:[0,1]
	s_nop 0
	v_pk_mul_f32 v[12:13], v[54:55], v[12:13] op_sel:[1,0]
	s_nop 0
	v_pk_fma_f32 v[12:13], v[20:21], v[12:13], v[64:65]
	v_lshlrev_b32_e32 v64, 16, v4
	v_cvt_pk_bf16_f32 v8, v12, v13
	ds_write_b16 v58, v8 offset:2176
	ds_write_b16_d16_hi v58, v8 offset:2448
	v_lshlrev_b32_e32 v8, 16, v9
	v_and_b32_e32 v9, 0xffff0000, v9
	v_pk_add_f32 v[8:9], v[8:9], v[54:55] op_sel_hi:[1,0] neg_lo:[0,1] neg_hi:[0,1]
	v_and_b32_e32 v65, 0xffff0000, v4
	v_pk_mul_f32 v[8:9], v[54:55], v[8:9] op_sel:[1,0]
	v_pk_add_f32 v[64:65], v[64:65], v[54:55] op_sel_hi:[1,0] neg_lo:[0,1] neg_hi:[0,1]
	v_pk_fma_f32 v[8:9], v[22:23], v[8:9], v[66:67]
	v_pk_mul_f32 v[64:65], v[54:55], v[64:65] op_sel:[1,0]
	v_cvt_pk_bf16_f32 v8, v8, v9
	ds_write_b16 v58, v8 offset:2720
	ds_write_b16_d16_hi v58, v8 offset:2992
	v_lshlrev_b32_e32 v8, 16, v10
	v_and_b32_e32 v9, 0xffff0000, v10
	v_pk_add_f32 v[8:9], v[8:9], v[54:55] op_sel_hi:[1,0] neg_lo:[0,1] neg_hi:[0,1]
	s_nop 0
	v_pk_mul_f32 v[8:9], v[54:55], v[8:9] op_sel:[1,0]
	s_nop 0
	v_pk_fma_f32 v[8:9], v[16:17], v[8:9], v[32:33]
	s_nop 0
	v_cvt_pk_bf16_f32 v8, v8, v9
	ds_write_b16 v58, v8 offset:3264
	ds_write_b16_d16_hi v58, v8 offset:3536
	v_lshlrev_b32_e32 v8, 16, v11
	v_and_b32_e32 v9, 0xffff0000, v11
	v_pk_add_f32 v[8:9], v[8:9], v[54:55] op_sel_hi:[1,0] neg_lo:[0,1] neg_hi:[0,1]
	s_nop 0
	v_pk_mul_f32 v[8:9], v[54:55], v[8:9] op_sel:[1,0]
	s_nop 0
	v_pk_fma_f32 v[8:9], v[18:19], v[8:9], v[34:35]
	s_nop 0
	v_cvt_pk_bf16_f32 v8, v8, v9
	ds_write_b16 v58, v8 offset:3808
	ds_write_b16_d16_hi v58, v8 offset:4080
	s_nop 0
	s_waitcnt vmcnt(0)
; #define LAS __attribute__((address_space(3)))
; DI unsigned pk2(float lo, float hi) { f32x2 v = {lo, hi}; bf16v2 r = __builtin_convertvector(v, bf16v2); return __builtin_bit_cast(unsigned, r); }
; DI float bflo(unsigned w) { return __uint_as_float(w << 16); }
; DI float bfhi(unsigned w) { return __uint_as_float(w & 0xffff0000u); }
; DI void phase_spatial(LAS unsigned char* lds, const bf16_t* GV, bf16_t* UG, const f32x2* STATS, const float* ln_w, const float* ln_b, const float* w_s, const float* b_s, int G) {
;     ...
;                 for (int w = 0; w < 4; ++w) { const float y0 = (bflo(aw[w]) - st.x) * st.y * wv[2 * w] + bv[2 * w], y1 = (bfhi(aw[w]) - st.x) * st.y * wv[2 * w + 1] + bv[2 * w + 1];
;                     const unsigned pk = pk2(y0, y1); const int cc = 32 * cq + 8 * q + 2 * w;
;                     VL[cc * 136 + s] = (bf16_t)(pk & 0xffffu); VL[(cc + 1) * 136 + s] = (bf16_t)(pk >> 16); } }
;             if (g != g_last) {
;                 const int t = tid >> 2, sq = tid & 3; const float* wp = w_s + ((size_t)g * 128 + t) * 128 + 32 * sq;
; #pragma unroll
;                 for (int q = 0; q < 4; ++q) { const f32x4 x0 = *(const f32x4*)(wp + 8 * q), x1 = *(const f32x4*)(wp + 8 * q + 4);
;                     *(LAS u32x4*)(WS + t * 136 + 32 * sq + 8 * q) = (u32x4){pk2(x0.x, x0.y), pk2(x0.z, x0.w), pk2(x1.x, x1.y), pk2(x1.z, x1.w)}; }
;                 g_last = g; }
	v_pk_fma_f32 v[32:33], v[92:93], v[64:65], v[108:109]
	s_nop 0
	v_cvt_pk_bf16_f32 v4, v32, v33
	ds_write_b16 v58, v4 offset:4352
	ds_write_b16_d16_hi v58, v4 offset:4624
	v_lshlrev_b32_e32 v4, 16, v5
	v_and_b32_e32 v5, 0xffff0000, v5
	v_pk_add_f32 v[4:5], v[4:5], v[54:55] op_sel_hi:[1,0] neg_lo:[0,1] neg_hi:[0,1]
	s_nop 0
	v_pk_mul_f32 v[4:5], v[54:55], v[4:5] op_sel:[1,0]
	s_nop 0
	v_pk_fma_f32 v[4:5], v[94:95], v[4:5], v[110:111]
	s_nop 0
	v_cvt_pk_bf16_f32 v4, v4, v5
	ds_write_b16 v58, v4 offset:4896
	ds_write_b16_d16_hi v58, v4 offset:5168
	v_lshlrev_b32_e32 v4, 16, v6
	v_and_b32_e32 v5, 0xffff0000, v6
	v_pk_add_f32 v[4:5], v[4:5], v[54:55] op_sel_hi:[1,0] neg_lo:[0,1] neg_hi:[0,1]
	s_nop 0
	v_pk_mul_f32 v[4:5], v[54:55], v[4:5] op_sel:[1,0]
	s_nop 0
	v_pk_fma_f32 v[4:5], v[88:89], v[4:5], v[104:105]
	s_nop 0
	v_cvt_pk_bf16_f32 v4, v4, v5
	ds_write_b16 v58, v4 offset:5440
	ds_write_b16_d16_hi v58, v4 offset:5712
	v_lshlrev_b32_e32 v4, 16, v7
	v_and_b32_e32 v5, 0xffff0000, v7
	v_pk_add_f32 v[4:5], v[4:5], v[54:55] op_sel_hi:[1,0] neg_lo:[0,1] neg_hi:[0,1]
	s_nop 0
	v_pk_mul_f32 v[4:5], v[54:55], v[4:5] op_sel:[1,0]
	s_nop 0
	v_pk_fma_f32 v[4:5], v[90:91], v[4:5], v[106:107]
	s_nop 0
	v_cvt_pk_bf16_f32 v4, v4, v5
	ds_write_b16 v58, v4 offset:5984
	ds_write_b16_d16_hi v58, v4 offset:6256
	v_lshlrev_b32_e32 v4, 16, v0
	v_and_b32_e32 v5, 0xffff0000, v0
	v_pk_add_f32 v[4:5], v[4:5], v[54:55] op_sel_hi:[1,0] neg_lo:[0,1] neg_hi:[0,1]
	s_nop 0
	v_pk_mul_f32 v[4:5], v[54:55], v[4:5] op_sel:[1,0]
	s_nop 0
	v_pk_fma_f32 v[4:5], v[84:85], v[4:5], v[100:101]
	s_nop 0
	v_cvt_pk_bf16_f32 v0, v4, v5
	ds_write_b16 v58, v0 offset:6528
	ds_write_b16_d16_hi v58, v0 offset:6800
	v_lshlrev_b32_e32 v0, 16, v1
	v_and_b32_e32 v1, 0xffff0000, v1
	v_pk_add_f32 v[0:1], v[0:1], v[54:55] op_sel_hi:[1,0] neg_lo:[0,1] neg_hi:[0,1]
	s_nop 0
	v_pk_mul_f32 v[0:1], v[54:55], v[0:1] op_sel:[1,0]
	s_nop 0
	v_pk_fma_f32 v[0:1], v[86:87], v[0:1], v[102:103]
	s_nop 0
	v_cvt_pk_bf16_f32 v0, v0, v1
	ds_write_b16 v58, v0 offset:7072
	ds_write_b16_d16_hi v58, v0 offset:7344
	v_lshlrev_b32_e32 v0, 16, v2
	v_and_b32_e32 v1, 0xffff0000, v2
	v_pk_add_f32 v[0:1], v[0:1], v[54:55] op_sel_hi:[1,0] neg_lo:[0,1] neg_hi:[0,1]
	s_nop 0
	v_pk_mul_f32 v[0:1], v[54:55], v[0:1] op_sel:[1,0]
	s_nop 0
	v_pk_fma_f32 v[0:1], v[80:81], v[0:1], v[96:97]
	s_nop 0
	v_cvt_pk_bf16_f32 v0, v0, v1
	ds_write_b16 v58, v0 offset:7616
	ds_write_b16_d16_hi v58, v0 offset:7888
	v_lshlrev_b32_e32 v0, 16, v3
	v_and_b32_e32 v1, 0xffff0000, v3
	v_pk_add_f32 v[0:1], v[0:1], v[54:55] op_sel_hi:[1,0] neg_lo:[0,1] neg_hi:[0,1]
	s_nop 0
	v_pk_mul_f32 v[0:1], v[54:55], v[0:1] op_sel:[1,0]
	s_nop 0
	v_pk_fma_f32 v[0:1], v[82:83], v[0:1], v[98:99]
	s_nop 0
	v_cvt_pk_bf16_f32 v0, v0, v1
	ds_write_b16 v58, v0 offset:8160
	ds_write_b16_d16_hi v58, v0 offset:8432
	s_cbranch_scc1 .LBB0_135
	s_mov_b32 s13, s72
	v_lshl_add_u64 v[0:1], s[12:13], 0, v[40:41]
	v_lshlrev_b64 v[0:1], 9, v[0:1]
	v_lshl_add_u64 v[16:17], v[46:47], 0, v[0:1]
	global_load_dwordx4 v[0:3], v[16:17], off offset:48
	global_load_dwordx4 v[4:7], v[16:17], off offset:32
	global_load_dwordx4 v[8:11], v[16:17], off offset:16
	global_load_dwordx4 v[12:15], v[16:17], off
	s_mov_b32 s16, s17
	s_waitcnt vmcnt(2)
	v_cvt_pk_bf16_f32 v4, v4, v5
	v_cvt_pk_bf16_f32 v5, v6, v7
	s_waitcnt vmcnt(0)
	v_cvt_pk_bf16_f32 v12, v12, v13
	v_cvt_pk_bf16_f32 v13, v14, v15
	v_cvt_pk_bf16_f32 v14, v8, v9
	v_cvt_pk_bf16_f32 v15, v10, v11
	v_cvt_pk_bf16_f32 v6, v0, v1
	v_cvt_pk_bf16_f32 v7, v2, v3
	ds_write_b128 v56, v[12:15] offset:34816
	ds_write_b128 v56, v[4:7] offset:34832
	global_load_dwordx4 v[0:3], v[16:17], off offset:112
	global_load_dwordx4 v[4:7], v[16:17], off offset:96
	global_load_dwordx4 v[8:11], v[16:17], off offset:80
	global_load_dwordx4 v[12:15], v[16:17], off offset:64
	s_waitcnt vmcnt(2)
	v_cvt_pk_bf16_f32 v4, v4, v5
	v_cvt_pk_bf16_f32 v5, v6, v7
	s_waitcnt vmcnt(0)
	v_cvt_pk_bf16_f32 v12, v12, v13
	v_cvt_pk_bf16_f32 v13, v14, v15
	v_cvt_pk_bf16_f32 v14, v8, v9
	v_cvt_pk_bf16_f32 v15, v10, v11
	v_cvt_pk_bf16_f32 v6, v0, v1
	v_cvt_pk_bf16_f32 v7, v2, v3
	ds_write_b128 v56, v[12:15] offset:34848
	ds_write_b128 v56, v[4:7] offset:34864
	s_branch .LBB0_135
